# speedup vs baseline: 1.0084x; 1.0009x over previous
; #define MFMA16(a, b, c) __builtin_amdgcn_mfma_f32_16x16x32_bf16((a), (b), (c), 0, 0, 0)
; __device__ __forceinline__ void attn_block(const Params& p, int bt_raw, char* smem) {
;     ...
;   const int hq = kvh * 4 + (fr >> 2);
;   const float slope2 = exp2f(-(float)(hq + 1)) * 1.4426950408889634f;
;   int tq[2], dq[2];
;   bf16x8 qf[2][4];
; #pragma unroll
;   for (int mt = 0; mt < 2; ++mt) {
;     tq[mt] = t0 + mt * 4 + (fr & 3);
;     dq[mt] = tq[mt] - fq * 4;
;     const u16* zr = Z + ((long)(b * SEQ + tq[mt])) * LDZ0;
;     const u16* qp = zr + 3072 + hq * 128 + fq * 8;
; #pragma unroll
;     for (int kk = 0; kk < 4; ++kk) qf[mt][kk] = *(const bf16x8*)(qp + kk * 32);
;   }
;   unsigned graw[2][2];
; #pragma unroll
;   for (int mt = 0; mt < 2; ++mt) {
;     const u16* gp_ = Z + ((long)(b * SEQ + tq[mt])) * LDZ0 + 6656 + hq;
;     graw[mt][0] = (unsigned)gp_[0] | ((unsigned)gp_[8] << 16);
;     graw[mt][1] = (unsigned)gp_[16];
;   }
;     ...
;   f32x4 O[8][2];
;   {
;     const float M2 = p.B1P[512];
;     const int nmax = (t0 + 7 - 31) >> 4;
;     const int ns8 = (t0 + 7 >= 31) ? (nmax >> 4) + 1 : 0;
;     const u16* kcb = p.KC + (long)(b * 2 + kvh) * 128 * 128;
;     const u16* vcb = p.VCT + (long)(b * 2 + kvh) * 4 * 4096;
;     f32x4 sc[2][8];
; #pragma unroll
;     for (int a = 0; a < 8; ++a) { sc[0][a] = f32x4{0.f, 0.f, 0.f, 0.f}; sc[1][a] = sc[0][a]; }
; #pragma unroll
;     for (int a = 0; a < 8; ++a) {
;       if (a < ns8) {
;         const u16* kr = kcb + (a * 16 + fr) * 128 + fq * 8;
; #pragma unroll
;         for (int kk = 0; kk < 4; ++kk) {
;           bf16x8 kf = *(const bf16x8*)(kr + kk * 32);
;           sc[0][a] = MFMA16(kf, qf[0][kk], sc[0][a]);
;           sc[1][a] = MFMA16(kf, qf[1][kk], sc[1][a]);
;         }
;       }
;     }
.LBB0_262:
	s_lshr_b32 s46, s44, 5
	s_and_b32 s2, s46, 24
	v_mov_b32_e32 v181, v194
	s_add_i32 s2, s2, s44
	s_lshl_b32 s2, s2, 6
	v_ashrrev_i32_e32 v180, 6, v181
	s_and_b32 s45, s2, 0x7c0
	v_lshlrev_b32_e32 v192, 3, v180
	s_ashr_i32 s48, s44, 6
	v_add_u32_e32 v201, s45, v192
	v_and_b32_e32 v193, 3, v181
	s_bfe_u32 s20, s44, 0x10005
	v_bfe_u32 v0, v181, 2, 2
	v_or_b32_e32 v137, v201, v193
	s_lshl_b32 s4, s48, 11
	v_lshl_or_b32 v149, s20, 2, v0
	v_add_u32_e32 v150, s4, v137
	v_mad_i64_i32 v[152:153], s[2:3], v150, s35, v[146:147]
	v_lshlrev_b32_e32 v144, 8, v149
	v_or_b32_e32 v139, 4, v137
	v_lshl_add_u64 v[0:1], v[152:153], 0, v[144:145]
	v_and_b32_e32 v32, 48, v181
	v_mov_b32_e32 v33, v145
	v_add_u32_e32 v148, s4, v139
	v_lshl_add_u64 v[0:1], v[0:1], 0, v[32:33]
	v_mad_i64_i32 v[154:155], s[2:3], v148, s35, v[146:147]
	s_waitcnt vmcnt(10)
	v_add_co_u32_e32 v8, vcc, s36, v0
	s_waitcnt vmcnt(8)
	v_lshl_add_u64 v[16:17], v[154:155], 0, v[144:145]
	v_addc_co_u32_e32 v9, vcc, 0, v1, vcc
	v_lshl_add_u64 v[16:17], v[16:17], 0, v[32:33]
	v_add_co_u32_e32 v24, vcc, s36, v16
	v_lshlrev_b32_e32 v144, 1, v149
	s_nop 0
	v_addc_co_u32_e32 v25, vcc, 0, v17, vcc
	v_lshl_add_u64 v[34:35], v[152:153], 0, v[144:145]
	v_lshl_add_u64 v[36:37], v[34:35], 0, s[22:23]
	v_add_co_u32_e32 v34, vcc, s37, v34
	v_lshl_add_u64 v[38:39], v[154:155], 0, v[144:145]
	s_nop 0
	v_addc_co_u32_e32 v35, vcc, 0, v35, vcc
	v_lshl_add_u64 v[12:13], v[0:1], 0, s[18:19]
	v_lshl_add_u64 v[28:29], v[16:17], 0, s[18:19]
	v_lshl_add_u64 v[40:41], v[38:39], 0, s[22:23]
	v_add_co_u32_e32 v38, vcc, s37, v38
	global_load_dwordx4 v[0:3], v[12:13], off offset:64
	global_load_dwordx4 v[4:7], v[12:13], off offset:128
	s_nop 0
	global_load_dwordx4 v[8:11], v[8:9], off offset:2048
	s_nop 0
	global_load_dwordx4 v[12:15], v[12:13], off offset:192
	s_nop 0
	global_load_dwordx4 v[16:19], v[28:29], off offset:64
	global_load_dwordx4 v[20:23], v[28:29], off offset:128
	s_nop 0
	global_load_dwordx4 v[24:27], v[24:25], off offset:2048
	s_nop 0
	global_load_dwordx4 v[28:31], v[28:29], off offset:192
	v_addc_co_u32_e32 v39, vcc, 0, v39, vcc
	global_load_ushort v138, v[34:35], off offset:1024
	global_load_ushort v182, v[36:37], off offset:16
	global_load_ushort v136, v[38:39], off offset:1024
	global_load_ushort v183, v[40:41], off offset:16
	global_load_ushort v199, v[40:41], off offset:32
	global_load_ushort v200, v[36:37], off offset:32
	v_readlane_b32 s4, v248, 2
	v_readlane_b32 s6, v248, 4
	v_readlane_b32 s7, v248, 5
	s_lshl_b32 s2, s48, 1
	v_readlane_b32 s64, v248, 10
	s_or_b32 s2, s2, s20
	v_readlane_b32 s65, v248, 11
	v_readlane_b32 s66, v248, 12
	global_load_dword v128, v145, s[6:7] offset:2048
	v_readlane_b32 s67, v248, 13
	v_readlane_b32 s76, v248, 22
	v_readlane_b32 s77, v248, 23
	v_subrev_u32_e32 v34, 24, v201
	s_ashr_i32 s3, s2, 31
	v_readlane_b32 s78, v248, 24
	v_readlane_b32 s79, v248, 25
	s_mov_b64 s[64:65], s[76:77]
	v_ashrrev_i32_e32 v34, 8, v34
	s_lshl_b64 s[28:29], s[2:3], 15
	v_or_b32_e32 v202, 7, v201
	s_mov_b64 s[66:67], s[78:79]
	v_readlane_b32 s5, v248, 3
	v_and_b32_e32 v206, 15, v181
	v_add_u32_e32 v34, 1, v34
	v_cmp_lt_i32_e32 vcc, 30, v202
	s_add_u32 s4, s66, s28
	s_addc_u32 s5, s67, s29
	v_cndmask_b32_e32 v60, 0, v34, vcc
	v_lshlrev_b32_e32 v98, 7, v206
	v_lshl_add_u64 v[96:97], s[4:5], 0, v[32:33]
	v_cmp_lt_i32_e64 s[10:11], 0, v60
	v_lshlrev_b32_e32 v144, 1, v98
	v_mov_b32_e32 v32, 0
	v_mov_b32_e32 v33, 0
	v_mov_b32_e32 v34, 0
	v_mov_b32_e32 v35, 0
	v_mov_b32_e32 v64, 0
	v_mov_b32_e32 v65, 0
	v_mov_b32_e32 v66, 0
	v_mov_b32_e32 v67, 0
	v_readlane_b32 s68, v248, 14
	v_readlane_b32 s69, v248, 15
	v_readlane_b32 s70, v248, 16
	v_readlane_b32 s71, v248, 17
	v_readlane_b32 s72, v248, 18
	v_readlane_b32 s73, v248, 19
	v_readlane_b32 s74, v248, 20
	v_readlane_b32 s75, v248, 21
	s_and_saveexec_b64 s[4:5], s[10:11]
	s_cbranch_execz .LBB0_264
	v_lshl_add_u64 v[48:49], v[96:97], 0, v[144:145]
	global_load_dwordx4 v[32:35], v[48:49], off
	global_load_dwordx4 v[36:39], v[48:49], off offset:64
	global_load_dwordx4 v[212:215], v[48:49], off offset:128
	global_load_dwordx4 v[216:219], v[48:49], off offset:192
	s_waitcnt vmcnt(3)
	v_mfma_f32_16x16x32_bf16 v[40:43], v[32:35], v[8:11], 0
	v_mfma_f32_16x16x32_bf16 v[32:35], v[32:35], v[24:27], 0
	s_waitcnt vmcnt(2)
	v_mfma_f32_16x16x32_bf16 v[40:43], v[36:39], v[0:3], v[40:43]
	v_mfma_f32_16x16x32_bf16 v[32:35], v[36:39], v[16:19], v[32:35]
	s_waitcnt vmcnt(1)
	v_mfma_f32_16x16x32_bf16 v[40:43], v[212:215], v[4:7], v[40:43]
	v_mfma_f32_16x16x32_bf16 v[32:35], v[212:215], v[20:23], v[32:35]
	s_waitcnt vmcnt(0)
	v_mfma_f32_16x16x32_bf16 v[64:67], v[216:219], v[12:15], v[40:43]
	v_mfma_f32_16x16x32_bf16 v[32:35], v[216:219], v[28:31], v[32:35]
.LBB0_264:
	s_or_b64 exec, exec, s[4:5]
	v_cmp_lt_i32_e32 vcc, 1, v60
	v_mov_b32_e32 v68, 0
	v_mov_b32_e32 v36, 0
	v_mov_b32_e32 v37, 0
	v_mov_b32_e32 v38, 0
	v_mov_b32_e32 v39, 0
	v_mov_b32_e32 v76, 0
	v_mov_b32_e32 v77, 0
	v_mov_b32_e32 v78, 0
	v_mov_b32_e32 v79, 0
	s_and_saveexec_b64 s[4:5], vcc
	s_cbranch_execz .LBB0_266
	v_lshl_add_u64 v[36:37], v[96:97], 0, v[144:145]
	v_add_co_u32_e32 v52, vcc, 0x1000, v36
	s_nop 1
	v_addc_co_u32_e32 v53, vcc, 0, v37, vcc
	global_load_dwordx4 v[36:39], v[52:53], off
	global_load_dwordx4 v[40:43], v[52:53], off offset:64
	global_load_dwordx4 v[212:215], v[52:53], off offset:128
	global_load_dwordx4 v[216:219], v[52:53], off offset:192
	s_waitcnt vmcnt(3)
	v_mfma_f32_16x16x32_bf16 v[44:47], v[36:39], v[8:11], 0
	v_mfma_f32_16x16x32_bf16 v[36:39], v[36:39], v[24:27], 0
	s_waitcnt vmcnt(2)
	v_mfma_f32_16x16x32_bf16 v[44:47], v[40:43], v[0:3], v[44:47]
	v_mfma_f32_16x16x32_bf16 v[36:39], v[40:43], v[16:19], v[36:39]
	s_waitcnt vmcnt(1)
	v_mfma_f32_16x16x32_bf16 v[44:47], v[212:215], v[4:7], v[44:47]
	v_mfma_f32_16x16x32_bf16 v[36:39], v[212:215], v[20:23], v[36:39]
	s_waitcnt vmcnt(0)
	v_mfma_f32_16x16x32_bf16 v[76:79], v[216:219], v[12:15], v[44:47]
	v_mfma_f32_16x16x32_bf16 v[36:39], v[216:219], v[28:31], v[36:39]
; #define MFMA16(a, b, c) __builtin_amdgcn_mfma_f32_16x16x32_bf16((a), (b), (c), 0, 0, 0)
; __device__ __forceinline__ void attn_block(const Params& p, int bt_raw, char* smem) {
;     ...
; #pragma unroll
;     for (int a = 0; a < 8; ++a) {
;       if (a < ns8) {
;         const u16* kr = kcb + (a * 16 + fr) * 128 + fq * 8;
; #pragma unroll
;         for (int kk = 0; kk < 4; ++kk) {
;           bf16x8 kf = *(const bf16x8*)(kr + kk * 32);
;           sc[0][a] = MFMA16(kf, qf[0][kk], sc[0][a]);
;           sc[1][a] = MFMA16(kf, qf[1][kk], sc[1][a]);
;         }
;       }
;     }
.LBB0_266:
	s_or_b64 exec, exec, s[4:5]
	v_cmp_lt_i32_e64 s[8:9], 2, v60
	v_mov_b32_e32 v69, 0
	v_mov_b32_e32 v70, 0
	v_mov_b32_e32 v71, 0
	v_mov_b32_e32 v40, 0
	v_mov_b32_e32 v41, 0
	v_mov_b32_e32 v42, 0
	v_mov_b32_e32 v43, 0
	s_and_saveexec_b64 s[4:5], s[8:9]
	s_cbranch_execz .LBB0_268
	v_lshl_add_u64 v[40:41], v[96:97], 0, v[144:145]
	v_add_co_u32_e32 v56, vcc, 0x2000, v40
	s_nop 1
	v_addc_co_u32_e32 v57, vcc, 0, v41, vcc
	global_load_dwordx4 v[40:43], v[56:57], off
	global_load_dwordx4 v[44:47], v[56:57], off offset:64
	global_load_dwordx4 v[212:215], v[56:57], off offset:128
	global_load_dwordx4 v[216:219], v[56:57], off offset:192
	s_waitcnt vmcnt(3)
	v_mfma_f32_16x16x32_bf16 v[48:51], v[40:43], v[8:11], 0
	v_mfma_f32_16x16x32_bf16 v[40:43], v[40:43], v[24:27], 0
	s_waitcnt vmcnt(2)
	v_mfma_f32_16x16x32_bf16 v[48:51], v[44:47], v[0:3], v[48:51]
	v_mfma_f32_16x16x32_bf16 v[40:43], v[44:47], v[16:19], v[40:43]
	s_waitcnt vmcnt(1)
	v_mfma_f32_16x16x32_bf16 v[48:51], v[212:215], v[4:7], v[48:51]
	v_mfma_f32_16x16x32_bf16 v[40:43], v[212:215], v[20:23], v[40:43]
	s_waitcnt vmcnt(0)
	v_mfma_f32_16x16x32_bf16 v[68:71], v[216:219], v[12:15], v[48:51]
	v_mfma_f32_16x16x32_bf16 v[40:43], v[216:219], v[28:31], v[40:43]
.LBB0_268:
	s_or_b64 exec, exec, s[4:5]
	v_cmp_lt_i32_e32 vcc, 3, v60
	v_mov_b32_e32 v72, 0
	v_mov_b32_e32 v80, 0
	v_mov_b32_e32 v81, 0
	v_mov_b32_e32 v82, 0
	v_mov_b32_e32 v83, 0
	v_mov_b32_e32 v44, 0
	v_mov_b32_e32 v45, 0
	v_mov_b32_e32 v46, 0
	v_mov_b32_e32 v47, 0
	s_and_saveexec_b64 s[4:5], vcc
	s_cbranch_execz .LBB0_270
	v_lshl_add_u64 v[44:45], v[96:97], 0, v[144:145]
	v_add_co_u32_e32 v62, vcc, 0x3000, v44
	s_nop 1
	v_addc_co_u32_e32 v63, vcc, 0, v45, vcc
	global_load_dwordx4 v[44:47], v[62:63], off
	global_load_dwordx4 v[48:51], v[62:63], off offset:64
	global_load_dwordx4 v[212:215], v[62:63], off offset:128
	global_load_dwordx4 v[216:219], v[62:63], off offset:192
	s_waitcnt vmcnt(3)
	v_mfma_f32_16x16x32_bf16 v[52:55], v[44:47], v[8:11], 0
	v_mfma_f32_16x16x32_bf16 v[44:47], v[44:47], v[24:27], 0
	s_waitcnt vmcnt(2)
	v_mfma_f32_16x16x32_bf16 v[52:55], v[48:51], v[0:3], v[52:55]
	v_mfma_f32_16x16x32_bf16 v[44:47], v[48:51], v[16:19], v[44:47]
	s_waitcnt vmcnt(1)
	v_mfma_f32_16x16x32_bf16 v[52:55], v[212:215], v[4:7], v[52:55]
	v_mfma_f32_16x16x32_bf16 v[44:47], v[212:215], v[20:23], v[44:47]
	s_waitcnt vmcnt(0)
	v_mfma_f32_16x16x32_bf16 v[80:83], v[216:219], v[12:15], v[52:55]
	v_mfma_f32_16x16x32_bf16 v[44:47], v[216:219], v[28:31], v[44:47]
.LBB0_270:
	s_or_b64 exec, exec, s[4:5]
	v_cmp_lt_i32_e64 s[6:7], 4, v60
	v_mov_b32_e32 v73, 0
	v_mov_b32_e32 v74, 0
	v_mov_b32_e32 v75, 0
	v_mov_b32_e32 v48, 0
	v_mov_b32_e32 v49, 0
	v_mov_b32_e32 v50, 0
	v_mov_b32_e32 v51, 0
	s_and_saveexec_b64 s[4:5], s[6:7]
	s_cbranch_execz .LBB0_272
	v_lshl_add_u64 v[48:49], v[96:97], 0, v[144:145]
	v_add_co_u32_e32 v62, vcc, 0x4000, v48
	s_nop 1
	v_addc_co_u32_e32 v63, vcc, 0, v49, vcc
	global_load_dwordx4 v[48:51], v[62:63], off
	global_load_dwordx4 v[52:55], v[62:63], off offset:64
	global_load_dwordx4 v[212:215], v[62:63], off offset:128
	global_load_dwordx4 v[216:219], v[62:63], off offset:192
	s_waitcnt vmcnt(3)
	v_mfma_f32_16x16x32_bf16 v[56:59], v[48:51], v[8:11], 0
	v_mfma_f32_16x16x32_bf16 v[48:51], v[48:51], v[24:27], 0
	s_waitcnt vmcnt(2)
	v_mfma_f32_16x16x32_bf16 v[56:59], v[52:55], v[0:3], v[56:59]
	v_mfma_f32_16x16x32_bf16 v[48:51], v[52:55], v[16:19], v[48:51]
	s_waitcnt vmcnt(1)
	v_mfma_f32_16x16x32_bf16 v[56:59], v[212:215], v[4:7], v[56:59]
	v_mfma_f32_16x16x32_bf16 v[48:51], v[212:215], v[20:23], v[48:51]
	s_waitcnt vmcnt(0)
	v_mfma_f32_16x16x32_bf16 v[72:75], v[216:219], v[12:15], v[56:59]
	v_mfma_f32_16x16x32_bf16 v[48:51], v[216:219], v[28:31], v[48:51]
; #define MFMA16(a, b, c) __builtin_amdgcn_mfma_f32_16x16x32_bf16((a), (b), (c), 0, 0, 0)
; __device__ __forceinline__ void attn_block(const Params& p, int bt_raw, char* smem) {
;     ...
; #pragma unroll
;     for (int a = 0; a < 8; ++a) {
;       if (a < ns8) {
;         const u16* kr = kcb + (a * 16 + fr) * 128 + fq * 8;
; #pragma unroll
;         for (int kk = 0; kk < 4; ++kk) {
;           bf16x8 kf = *(const bf16x8*)(kr + kk * 32);
;           sc[0][a] = MFMA16(kf, qf[0][kk], sc[0][a]);
;           sc[1][a] = MFMA16(kf, qf[1][kk], sc[1][a]);
;         }
;       }
;     }
.LBB0_272:
	s_or_b64 exec, exec, s[4:5]
	v_cmp_lt_i32_e32 vcc, 5, v60
	v_mov_b32_e32 v84, 0
	v_mov_b32_e32 v88, 0
	v_mov_b32_e32 v89, 0
	v_mov_b32_e32 v90, 0
	v_mov_b32_e32 v91, 0
	v_mov_b32_e32 v52, 0
	v_mov_b32_e32 v53, 0
	v_mov_b32_e32 v54, 0
	v_mov_b32_e32 v55, 0
	s_and_saveexec_b64 s[4:5], vcc
	s_cbranch_execz .LBB0_274
	v_lshl_add_u64 v[52:53], v[96:97], 0, v[144:145]
	v_add_co_u32_e32 v62, vcc, 0x5000, v52
	s_nop 1
	v_addc_co_u32_e32 v63, vcc, 0, v53, vcc
	global_load_dwordx4 v[52:55], v[62:63], off
	global_load_dwordx4 v[56:59], v[62:63], off offset:64
	global_load_dwordx4 v[212:215], v[62:63], off offset:128
	global_load_dwordx4 v[216:219], v[62:63], off offset:192
	s_waitcnt vmcnt(3)
	v_mfma_f32_16x16x32_bf16 v[86:89], v[52:55], v[8:11], 0
	v_mfma_f32_16x16x32_bf16 v[52:55], v[52:55], v[24:27], 0
	s_waitcnt vmcnt(2)
	v_mfma_f32_16x16x32_bf16 v[86:89], v[56:59], v[0:3], v[86:89]
	v_mfma_f32_16x16x32_bf16 v[52:55], v[56:59], v[16:19], v[52:55]
	s_waitcnt vmcnt(1)
	v_mfma_f32_16x16x32_bf16 v[86:89], v[212:215], v[4:7], v[86:89]
	v_mfma_f32_16x16x32_bf16 v[52:55], v[212:215], v[20:23], v[52:55]
	s_waitcnt vmcnt(0)
	v_mfma_f32_16x16x32_bf16 v[88:91], v[216:219], v[12:15], v[86:89]
	v_mfma_f32_16x16x32_bf16 v[52:55], v[216:219], v[28:31], v[52:55]
.LBB0_274:
	s_or_b64 exec, exec, s[4:5]
	v_cmp_lt_i32_e64 s[4:5], 6, v60
	v_mov_b32_e32 v85, 0
	s_nop 0
	v_mov_b32_e32 v86, 0
	v_mov_b32_e32 v87, 0
	v_mov_b32_e32 v56, 0
	v_mov_b32_e32 v57, 0
	v_mov_b32_e32 v58, 0
	v_mov_b32_e32 v59, 0
	s_and_saveexec_b64 s[12:13], s[4:5]
	s_cbranch_execz .LBB0_276
	v_lshl_add_u64 v[56:57], v[96:97], 0, v[144:145]
	v_add_co_u32_e32 v62, vcc, 0x6000, v56
	s_nop 1
	v_addc_co_u32_e32 v63, vcc, 0, v57, vcc
	global_load_dwordx4 v[56:59], v[62:63], off
	global_load_dwordx4 v[84:87], v[62:63], off offset:64
	global_load_dwordx4 v[212:215], v[62:63], off offset:128
	global_load_dwordx4 v[216:219], v[62:63], off offset:192
	s_waitcnt vmcnt(3)
	v_mfma_f32_16x16x32_bf16 v[92:95], v[56:59], v[8:11], 0
	v_mfma_f32_16x16x32_bf16 v[56:59], v[56:59], v[24:27], 0
	s_waitcnt vmcnt(2)
	v_mfma_f32_16x16x32_bf16 v[92:95], v[84:87], v[0:3], v[92:95]
	v_mfma_f32_16x16x32_bf16 v[56:59], v[84:87], v[16:19], v[56:59]
	s_waitcnt vmcnt(1)
	v_mfma_f32_16x16x32_bf16 v[84:87], v[212:215], v[4:7], v[92:95]
	v_mfma_f32_16x16x32_bf16 v[56:59], v[212:215], v[20:23], v[56:59]
	s_waitcnt vmcnt(0)
	v_mfma_f32_16x16x32_bf16 v[84:87], v[216:219], v[12:15], v[84:87]
	v_mfma_f32_16x16x32_bf16 v[56:59], v[216:219], v[28:31], v[56:59]
.LBB0_276:
	s_or_b64 exec, exec, s[12:13]
	v_cmp_lt_i32_e32 vcc, 7, v60
	v_mov_b32_e32 v92, 0
	v_mov_b32_e32 v93, 0
	v_mov_b32_e32 v94, 0
	v_mov_b32_e32 v95, 0
	v_mov_b32_e32 v60, 0
	v_mov_b32_e32 v61, 0
	v_mov_b32_e32 v62, 0
	v_mov_b32_e32 v63, 0
	s_and_saveexec_b64 s[12:13], vcc
	s_cbranch_execz .LBB0_278
	v_lshl_add_u64 v[60:61], v[96:97], 0, v[144:145]
	v_add_co_u32_e32 v96, vcc, 0x7000, v60
	s_nop 1
	v_addc_co_u32_e32 v97, vcc, 0, v61, vcc
	global_load_dwordx4 v[60:63], v[96:97], off
	global_load_dwordx4 v[92:95], v[96:97], off offset:64
	global_load_dwordx4 v[212:215], v[96:97], off offset:128
	global_load_dwordx4 v[216:219], v[96:97], off offset:192
	s_waitcnt vmcnt(3)
	v_mfma_f32_16x16x32_bf16 v[100:103], v[60:63], v[8:11], 0
	v_mfma_f32_16x16x32_bf16 v[60:63], v[60:63], v[24:27], 0
	s_waitcnt vmcnt(2)
	v_mfma_f32_16x16x32_bf16 v[100:103], v[92:95], v[0:3], v[100:103]
	v_mfma_f32_16x16x32_bf16 v[60:63], v[92:95], v[16:19], v[60:63]
	s_waitcnt vmcnt(1)
	v_mfma_f32_16x16x32_bf16 v[92:95], v[212:215], v[4:7], v[100:103]
	v_mfma_f32_16x16x32_bf16 v[60:63], v[212:215], v[20:23], v[60:63]
	s_waitcnt vmcnt(0)
	v_mfma_f32_16x16x32_bf16 v[92:95], v[216:219], v[12:15], v[92:95]
	v_mfma_f32_16x16x32_bf16 v[60:63], v[216:219], v[28:31], v[60:63]

; #define MFMA16(a, b, c) __builtin_amdgcn_mfma_f32_16x16x32_bf16((a), (b), (c), 0, 0, 0)
; #define GATE(brn, mt) sigmoidf_((brn) == 0 ? lo2f(graw[mt][0]) : (brn) == 1 ? hi2f(graw[mt][0]) : lo2f(graw[mt][1]))
; __device__ __forceinline__ void attn_block(const Params& p, int bt_raw, char* smem) {
;     ...
;       g0v[mt] = GATE(0, mt);
;     }
;     f32x4 Oc[2][8];
; #pragma unroll
;     for (int dt = 0; dt < 8; ++dt) { Oc[0][dt] = f32x4{0.f, 0.f, 0.f, 0.f}; Oc[1][dt] = Oc[0][dt]; }
; #pragma unroll
;     for (int ks = 0; ks < 4; ++ks) {
;       if (ks * 2 < ns8) {
;         bf16x8 pf[2];
; #pragma unroll
;         for (int mt = 0; mt < 2; ++mt) {
;           float pv[8];
; #pragma unroll
;           for (int j = 0; j < 4; ++j) {
;             pv[j] = sc[mt][ks * 2][j] * g0v[mt];
;             pv[4 + j] = sc[mt][ks * 2 + 1][j] * g0v[mt];
;           }
;           pf[mt] = as_bf16x8(pack8(pv));
;         }
; #pragma unroll
;         for (int dt = 0; dt < 8; ++dt) {
;           bf16x8 vf = *(const bf16x8*)(vcb + ks * 4096 + (dt * 16 + fr) * 32 + fq * 8);
;           Oc[0][dt] = MFMA16(vf, pf[0], Oc[0][dt]);
;           Oc[1][dt] = MFMA16(vf, pf[1], Oc[1][dt]);
;         }
;       }
.LBB0_310:
	s_or_b64 exec, exec, s[30:31]
	v_lshlrev_b32_e32 v32, 16, v138
	v_mul_f32_e32 v32, 0xbfb8aa3b, v32
	v_lshlrev_b32_e32 v33, 16, v136
	v_exp_f32_e32 v32, v32
	v_mul_f32_e32 v33, 0xbfb8aa3b, v33
	v_exp_f32_e32 v33, v33
	v_readlane_b32 s12, v248, 2
	v_add_f32_e32 v32, 1.0, v32
	v_rcp_f32_e32 v138, v32
	v_add_f32_e32 v32, 1.0, v33
	v_rcp_f32_e32 v136, v32
	v_lshlrev_b32_e32 v175, 3, v144
	v_readlane_b32 s13, v248, 3
	s_add_u32 s12, s12, s28
	v_lshlrev_b32_e32 v36, 5, v206
	s_waitcnt lgkmcnt(1)
	v_mov_b32_e32 v34, v145
	s_waitcnt lgkmcnt(0)
	v_mov_b32_e32 v35, v145
	s_addc_u32 s13, s13, s29
	v_lshlrev_b32_e32 v144, 1, v175
	v_mov_b32_e32 v32, v145
	v_mov_b32_e32 v33, v145
	v_lshlrev_b32_e32 v162, 1, v36
	v_mov_b64_e32 v[38:39], v[34:35]
	v_mov_b64_e32 v[46:47], v[34:35]
	v_mov_b64_e32 v[58:59], v[34:35]
	v_mov_b64_e32 v[62:63], v[34:35]
	v_mov_b64_e32 v[50:51], v[34:35]
	v_mov_b64_e32 v[42:43], v[34:35]
	v_mov_b64_e32 v[54:55], v[34:35]
	v_mov_b64_e32 v[66:67], v[34:35]
	v_mov_b64_e32 v[86:87], v[34:35]
	v_mov_b64_e32 v[82:83], v[34:35]
	v_mov_b64_e32 v[94:95], v[34:35]
	v_mov_b64_e32 v[90:91], v[34:35]
	v_mov_b64_e32 v[78:79], v[34:35]
	v_mov_b64_e32 v[70:71], v[34:35]
	v_mov_b64_e32 v[74:75], v[34:35]
	v_lshl_add_u64 v[156:157], s[12:13], 0, v[144:145]
	v_mov_b64_e32 v[36:37], v[32:33]
	v_mov_b64_e32 v[44:45], v[32:33]
	v_mov_b64_e32 v[56:57], v[32:33]
	v_mov_b64_e32 v[60:61], v[32:33]
	v_mov_b64_e32 v[48:49], v[32:33]
	v_mov_b64_e32 v[40:41], v[32:33]
	v_mov_b64_e32 v[52:53], v[32:33]
	v_mov_b64_e32 v[64:65], v[32:33]
	v_mov_b64_e32 v[84:85], v[32:33]
	v_mov_b64_e32 v[80:81], v[32:33]
	v_mov_b64_e32 v[92:93], v[32:33]
	v_mov_b64_e32 v[88:89], v[32:33]
	v_mov_b64_e32 v[76:77], v[32:33]
	v_mov_b64_e32 v[68:69], v[32:33]
	v_mov_b64_e32 v[72:73], v[32:33]
	v_readlane_b32 s14, v248, 4
	v_readlane_b32 s15, v248, 5
	s_and_saveexec_b64 s[12:13], s[10:11]
	s_cbranch_execz .LBB0_314
	v_mov_b32_e32 v163, v145
	v_lshl_add_u64 v[44:45], v[156:157], 0, v[162:163]
	global_load_dwordx4 v[32:35], v[44:45], off
	global_load_dwordx4 v[36:39], v[44:45], off offset:1024
	v_add_co_u32_e32 v210, vcc, s36, v44
	s_nop 1
	v_addc_co_u32_e32 v211, vcc, 0, v45, vcc
	global_load_dwordx4 v[212:215], v[210:211], off offset:3072
	global_load_dwordx4 v[216:219], v[44:45], off offset:2048
	global_load_dwordx4 v[220:223], v[44:45], off offset:3072
	global_load_dwordx4 v[224:227], v[210:211], off
	global_load_dwordx4 v[228:231], v[210:211], off offset:1024
	global_load_dwordx4 v[232:235], v[210:211], off offset:2048
	v_mul_f32_e32 v54, v151, v122
	v_mul_f32_e32 v55, v123, v174
	v_pk_mul_f32 v[40:41], v[138:139], v[126:127] op_sel_hi:[0,1]
	v_mul_f32_e32 v56, v138, v189
	v_pk_mul_f32 v[42:43], v[138:139], v[120:121] op_sel_hi:[0,1]
	v_pk_mul_f32 v[46:47], v[138:139], v[124:125] op_sel_hi:[0,1]
	v_pk_mul_f32 v[48:49], v[136:137], v[178:179] op_sel_hi:[0,1]
	v_mul_f32_e32 v57, v136, v190
	v_pk_mul_f32 v[50:51], v[136:137], v[172:173] op_sel_hi:[0,1]
	v_pk_mul_f32 v[52:53], v[136:137], v[176:177] op_sel_hi:[0,1]
	v_mul_f32_e32 v54, v138, v54
	v_cvt_pk_bf16_f32 v66, v40, v41
	v_mul_f32_e32 v40, v136, v55
	v_cvt_pk_bf16_f32 v65, v42, v43
	v_cvt_pk_bf16_f32 v67, v46, v47
	v_cvt_pk_bf16_f32 v121, v50, v51
	v_cvt_pk_bf16_f32 v64, v54, v56
	v_cvt_pk_bf16_f32 v122, v48, v49
	v_cvt_pk_bf16_f32 v123, v52, v53
	v_cvt_pk_bf16_f32 v120, v40, v57
	s_waitcnt vmcnt(7)
	v_mfma_f32_16x16x32_bf16 v[72:75], v[32:35], v[64:67], 0
	v_mfma_f32_16x16x32_bf16 v[52:55], v[32:35], v[120:123], 0
	s_waitcnt vmcnt(6)
	v_mfma_f32_16x16x32_bf16 v[68:71], v[36:39], v[64:67], 0
	v_mfma_f32_16x16x32_bf16 v[40:43], v[36:39], v[120:123], 0
	s_waitcnt vmcnt(4)
	v_mfma_f32_16x16x32_bf16 v[76:79], v[216:219], v[64:67], 0
	v_mfma_f32_16x16x32_bf16 v[48:51], v[216:219], v[120:123], 0
	s_waitcnt vmcnt(3)
	v_mfma_f32_16x16x32_bf16 v[88:91], v[220:223], v[64:67], 0
	v_mfma_f32_16x16x32_bf16 v[60:63], v[220:223], v[120:123], 0
	s_waitcnt vmcnt(2)
	v_mfma_f32_16x16x32_bf16 v[92:95], v[224:227], v[64:67], 0
	v_mfma_f32_16x16x32_bf16 v[56:59], v[224:227], v[120:123], 0
	s_waitcnt vmcnt(1)
	v_mfma_f32_16x16x32_bf16 v[80:83], v[228:231], v[64:67], 0
	v_mfma_f32_16x16x32_bf16 v[44:47], v[228:231], v[120:123], 0
	s_waitcnt vmcnt(0)
	v_mfma_f32_16x16x32_bf16 v[84:87], v[232:235], v[64:67], 0
	v_mfma_f32_16x16x32_bf16 v[36:39], v[232:235], v[120:123], 0
	v_mfma_f32_16x16x32_bf16 v[64:67], v[212:215], v[64:67], 0
	v_mfma_f32_16x16x32_bf16 v[32:35], v[212:215], v[120:123], 0
	s_or_b64 exec, exec, s[12:13]
	s_and_saveexec_b64 s[10:11], s[8:9]
	s_cbranch_execnz .LBB0_315

; #define MFMA16(a, b, c) __builtin_amdgcn_mfma_f32_16x16x32_bf16((a), (b), (c), 0, 0, 0)
; __device__ __forceinline__ void attn_block(const Params& p, int bt_raw, char* smem) {
;     ...
;     for (int ks = 0; ks < 4; ++ks) {
;       if (ks * 2 < ns8) {
;         bf16x8 pf[2];
; #pragma unroll
;         for (int mt = 0; mt < 2; ++mt) {
;           float pv[8];
; #pragma unroll
;           for (int j = 0; j < 4; ++j) {
;             pv[j] = sc[mt][ks * 2][j] * g0v[mt];
;             pv[4 + j] = sc[mt][ks * 2 + 1][j] * g0v[mt];
;           }
;           pf[mt] = as_bf16x8(pack8(pv));
;         }
; #pragma unroll
;         for (int dt = 0; dt < 8; ++dt) {
;           bf16x8 vf = *(const bf16x8*)(vcb + ks * 4096 + (dt * 16 + fr) * 32 + fq * 8);
;           Oc[0][dt] = MFMA16(vf, pf[0], Oc[0][dt]);
;           Oc[1][dt] = MFMA16(vf, pf[1], Oc[1][dt]);
;         }
;       }
.LBB0_313:
	v_mov_b32_e32 v163, v145
	v_lshl_add_u64 v[120:121], v[156:157], 0, v[162:163]
	s_mov_b64 s[6:7], 0x4000
	v_lshl_add_u64 v[122:123], v[120:121], 0, s[6:7]
	global_load_dwordx4 v[112:115], v[122:123], off offset:1024
	global_load_dwordx4 v[116:119], v[122:123], off offset:2048
	s_movk_i32 s6, 0x4000
	v_add_co_u32_e32 v210, vcc, s6, v120
	s_nop 1
	v_addc_co_u32_e32 v211, vcc, 0, v121, vcc
	v_add_co_u32_e32 v250, vcc, 0x5000, v120
	s_nop 1
	v_addc_co_u32_e32 v251, vcc, 0, v121, vcc
	global_load_dwordx4 v[212:215], v[210:211], off
	global_load_dwordx4 v[216:219], v[122:123], off offset:3072
	global_load_dwordx4 v[220:223], v[250:251], off
	global_load_dwordx4 v[224:227], v[250:251], off offset:1024
	global_load_dwordx4 v[228:231], v[250:251], off offset:2048
	global_load_dwordx4 v[232:235], v[250:251], off offset:3072
	v_pk_mul_f32 v[124:125], v[138:139], v[104:105] op_sel_hi:[0,1]
	v_pk_mul_f32 v[106:107], v[138:139], v[106:107] op_sel_hi:[0,1]
	v_pk_mul_f32 v[110:111], v[138:139], v[110:111] op_sel_hi:[0,1]
	v_pk_mul_f32 v[108:109], v[138:139], v[108:109] op_sel_hi:[0,1]
	v_pk_mul_f32 v[126:127], v[136:137], v[142:143] op_sel_hi:[0,1]
	v_pk_mul_f32 v[142:143], v[136:137], v[160:161] op_sel_hi:[0,1]
	v_pk_mul_f32 v[140:141], v[136:137], v[140:141] op_sel_hi:[0,1]
	v_pk_mul_f32 v[158:159], v[136:137], v[158:159] op_sel_hi:[0,1]
	v_cvt_pk_bf16_f32 v105, v124, v125
	v_cvt_pk_bf16_f32 v104, v106, v107
	v_cvt_pk_bf16_f32 v106, v110, v111
	v_cvt_pk_bf16_f32 v107, v108, v109
	v_cvt_pk_bf16_f32 v108, v126, v127
	v_cvt_pk_bf16_f32 v109, v140, v141
	v_cvt_pk_bf16_f32 v110, v142, v143
	v_cvt_pk_bf16_f32 v111, v158, v159
	s_waitcnt vmcnt(7)
	v_mfma_f32_16x16x32_bf16 v[68:71], v[112:115], v[104:107], v[68:71]
	v_mfma_f32_16x16x32_bf16 v[40:43], v[112:115], v[108:111], v[40:43]
	s_waitcnt vmcnt(6)
	v_mfma_f32_16x16x32_bf16 v[76:79], v[116:119], v[104:107], v[76:79]
	v_mfma_f32_16x16x32_bf16 v[48:51], v[116:119], v[108:111], v[48:51]
	s_waitcnt vmcnt(5)
	v_mfma_f32_16x16x32_bf16 v[72:75], v[212:215], v[104:107], v[72:75]
	v_mfma_f32_16x16x32_bf16 v[52:55], v[212:215], v[108:111], v[52:55]
	s_waitcnt vmcnt(4)
	v_mfma_f32_16x16x32_bf16 v[88:91], v[216:219], v[104:107], v[88:91]
	v_mfma_f32_16x16x32_bf16 v[60:63], v[216:219], v[108:111], v[60:63]
	s_waitcnt vmcnt(3)
	v_mfma_f32_16x16x32_bf16 v[92:95], v[220:223], v[104:107], v[92:95]
	v_mfma_f32_16x16x32_bf16 v[56:59], v[220:223], v[108:111], v[56:59]
	s_waitcnt vmcnt(2)
	v_mfma_f32_16x16x32_bf16 v[80:83], v[224:227], v[104:107], v[80:83]
	v_mfma_f32_16x16x32_bf16 v[44:47], v[224:227], v[108:111], v[44:47]
	s_waitcnt vmcnt(1)
	v_mfma_f32_16x16x32_bf16 v[84:87], v[228:231], v[104:107], v[84:87]
	v_mfma_f32_16x16x32_bf16 v[36:39], v[228:231], v[108:111], v[36:39]
	s_waitcnt vmcnt(0)
	v_mfma_f32_16x16x32_bf16 v[64:67], v[232:235], v[104:107], v[64:67]
	v_mfma_f32_16x16x32_bf16 v[32:35], v[232:235], v[108:111], v[32:35]
	s_or_b64 exec, exec, s[8:9]
	s_and_saveexec_b64 s[6:7], s[4:5]
	s_cbranch_execnz .LBB0_317
	s_branch .LBB0_318

; #define MFMA16(a, b, c) __builtin_amdgcn_mfma_f32_16x16x32_bf16((a), (b), (c), 0, 0, 0)
; __device__ __forceinline__ void attn_block(const Params& p, int bt_raw, char* smem) {
;     ...
;     for (int ks = 0; ks < 4; ++ks) {
;       if (ks * 2 < ns8) {
;         bf16x8 pf[2];
; #pragma unroll
;         for (int mt = 0; mt < 2; ++mt) {
;           float pv[8];
; #pragma unroll
;           for (int j = 0; j < 4; ++j) {
;             pv[j] = sc[mt][ks * 2][j] * g0v[mt];
;             pv[4 + j] = sc[mt][ks * 2 + 1][j] * g0v[mt];
;           }
;           pf[mt] = as_bf16x8(pack8(pv));
;         }
; #pragma unroll
;         for (int dt = 0; dt < 8; ++dt) {
;           bf16x8 vf = *(const bf16x8*)(vcb + ks * 4096 + (dt * 16 + fr) * 32 + fq * 8);
;           Oc[0][dt] = MFMA16(vf, pf[0], Oc[0][dt]);
;           Oc[1][dt] = MFMA16(vf, pf[1], Oc[1][dt]);
;         }
;       }
.LBB0_315:
	v_mov_b32_e32 v163, v145
	v_lshl_add_u64 v[172:173], v[156:157], 0, v[162:163]
	v_lshl_add_u64 v[176:177], v[172:173], 0, s[24:25]
	global_load_dwordx4 v[120:123], v[176:177], off offset:1024
	global_load_dwordx4 v[124:127], v[176:177], off offset:2048
	v_add_co_u32_e32 v210, vcc, s38, v172
	s_nop 1
	v_addc_co_u32_e32 v211, vcc, 0, v173, vcc
	v_add_co_u32_e32 v250, vcc, 0x3000, v172
	s_nop 1
	v_addc_co_u32_e32 v251, vcc, 0, v173, vcc
	global_load_dwordx4 v[212:215], v[210:211], off
	global_load_dwordx4 v[216:219], v[176:177], off offset:3072
	global_load_dwordx4 v[220:223], v[250:251], off
	global_load_dwordx4 v[224:227], v[250:251], off offset:1024
	global_load_dwordx4 v[228:231], v[250:251], off offset:2048
	global_load_dwordx4 v[232:235], v[250:251], off offset:3072
	v_pk_mul_f32 v[114:115], v[138:139], v[114:115] op_sel_hi:[0,1]
	v_pk_mul_f32 v[116:117], v[138:139], v[116:117] op_sel_hi:[0,1]
	v_pk_mul_f32 v[164:165], v[136:137], v[164:165] op_sel_hi:[0,1]
	v_pk_mul_f32 v[118:119], v[138:139], v[118:119] op_sel_hi:[0,1]
	v_pk_mul_f32 v[178:179], v[138:139], v[112:113] op_sel_hi:[0,1]
	v_pk_mul_f32 v[166:167], v[136:137], v[166:167] op_sel_hi:[0,1]
	v_pk_mul_f32 v[170:171], v[136:137], v[170:171] op_sel_hi:[0,1]
	v_pk_mul_f32 v[168:169], v[136:137], v[168:169] op_sel_hi:[0,1]
	v_cvt_pk_bf16_f32 v112, v114, v115
	v_cvt_pk_bf16_f32 v115, v116, v117
	v_cvt_pk_bf16_f32 v117, v164, v165
	v_cvt_pk_bf16_f32 v113, v178, v179
	v_cvt_pk_bf16_f32 v114, v118, v119
	v_cvt_pk_bf16_f32 v116, v166, v167
	v_cvt_pk_bf16_f32 v118, v170, v171
	v_cvt_pk_bf16_f32 v119, v168, v169
	s_waitcnt vmcnt(7)
	v_mfma_f32_16x16x32_bf16 v[68:71], v[120:123], v[112:115], v[68:71]
	v_mfma_f32_16x16x32_bf16 v[40:43], v[120:123], v[116:119], v[40:43]
	s_waitcnt vmcnt(6)
	v_mfma_f32_16x16x32_bf16 v[76:79], v[124:127], v[112:115], v[76:79]
	v_mfma_f32_16x16x32_bf16 v[48:51], v[124:127], v[116:119], v[48:51]
	s_waitcnt vmcnt(5)
	v_mfma_f32_16x16x32_bf16 v[72:75], v[212:215], v[112:115], v[72:75]
	v_mfma_f32_16x16x32_bf16 v[52:55], v[212:215], v[116:119], v[52:55]
	s_waitcnt vmcnt(4)
	v_mfma_f32_16x16x32_bf16 v[88:91], v[216:219], v[112:115], v[88:91]
	v_mfma_f32_16x16x32_bf16 v[60:63], v[216:219], v[116:119], v[60:63]
	s_waitcnt vmcnt(3)
	v_mfma_f32_16x16x32_bf16 v[92:95], v[220:223], v[112:115], v[92:95]
	v_mfma_f32_16x16x32_bf16 v[56:59], v[220:223], v[116:119], v[56:59]
	s_waitcnt vmcnt(2)
	v_mfma_f32_16x16x32_bf16 v[80:83], v[224:227], v[112:115], v[80:83]
	v_mfma_f32_16x16x32_bf16 v[44:47], v[224:227], v[116:119], v[44:47]
	s_waitcnt vmcnt(1)
	v_mfma_f32_16x16x32_bf16 v[84:87], v[228:231], v[112:115], v[84:87]
	v_mfma_f32_16x16x32_bf16 v[36:39], v[228:231], v[116:119], v[36:39]
	s_waitcnt vmcnt(0)
	v_mfma_f32_16x16x32_bf16 v[64:67], v[232:235], v[112:115], v[64:67]
	v_mfma_f32_16x16x32_bf16 v[32:35], v[232:235], v[116:119], v[32:35]
	s_or_b64 exec, exec, s[10:11]
	s_and_saveexec_b64 s[8:9], s[6:7]
	s_cbranch_execnz .LBB0_313

; #define MFMA16(a, b, c) __builtin_amdgcn_mfma_f32_16x16x32_bf16((a), (b), (c), 0, 0, 0)
; __device__ __forceinline__ void attn_block(const Params& p, int bt_raw, char* smem) {
;     ...
;     for (int ks = 0; ks < 4; ++ks) {
;       if (ks * 2 < ns8) {
;         bf16x8 pf[2];
; #pragma unroll
;         for (int mt = 0; mt < 2; ++mt) {
;           float pv[8];
; #pragma unroll
;           for (int j = 0; j < 4; ++j) {
;             pv[j] = sc[mt][ks * 2][j] * g0v[mt];
;             pv[4 + j] = sc[mt][ks * 2 + 1][j] * g0v[mt];
;           }
;           pf[mt] = as_bf16x8(pack8(pv));
;         }
; #pragma unroll
;         for (int dt = 0; dt < 8; ++dt) {
;           bf16x8 vf = *(const bf16x8*)(vcb + ks * 4096 + (dt * 16 + fr) * 32 + fq * 8);
;           Oc[0][dt] = MFMA16(vf, pf[0], Oc[0][dt]);
;           Oc[1][dt] = MFMA16(vf, pf[1], Oc[1][dt]);
;         }
;       }
.LBB0_317:
	v_mov_b32_e32 v163, v145
	v_lshl_add_u64 v[112:113], v[156:157], 0, v[162:163]
	s_mov_b64 s[4:5], 0x6000
	v_lshl_add_u64 v[114:115], v[112:113], 0, s[4:5]
	global_load_dwordx4 v[104:107], v[114:115], off offset:1024
	global_load_dwordx4 v[108:111], v[114:115], off offset:2048
	s_movk_i32 s4, 0x6000
	v_add_co_u32_e32 v210, vcc, s4, v112
	s_nop 1
	v_addc_co_u32_e32 v211, vcc, 0, v113, vcc
	v_add_co_u32_e32 v250, vcc, 0x7000, v112
	s_nop 1
	v_addc_co_u32_e32 v251, vcc, 0, v113, vcc
	global_load_dwordx4 v[212:215], v[210:211], off
	global_load_dwordx4 v[216:219], v[114:115], off offset:3072
	global_load_dwordx4 v[220:223], v[250:251], off
	global_load_dwordx4 v[224:227], v[250:251], off offset:1024
	global_load_dwordx4 v[228:231], v[250:251], off offset:2048
	global_load_dwordx4 v[232:235], v[250:251], off offset:3072
	v_pk_mul_f32 v[116:117], v[138:139], v[96:97] op_sel_hi:[0,1]
	v_pk_mul_f32 v[98:99], v[138:139], v[98:99] op_sel_hi:[0,1]
	v_pk_mul_f32 v[102:103], v[138:139], v[102:103] op_sel_hi:[0,1]
	v_pk_mul_f32 v[100:101], v[138:139], v[100:101] op_sel_hi:[0,1]
	v_pk_mul_f32 v[118:119], v[136:137], v[130:131] op_sel_hi:[0,1]
	v_pk_mul_f32 v[120:121], v[136:137], v[134:135] op_sel_hi:[0,1]
	v_pk_mul_f32 v[122:123], v[136:137], v[128:129] op_sel_hi:[0,1]
	v_pk_mul_f32 v[124:125], v[136:137], v[132:133] op_sel_hi:[0,1]
	v_cvt_pk_bf16_f32 v97, v116, v117
	v_cvt_pk_bf16_f32 v96, v98, v99
	v_cvt_pk_bf16_f32 v98, v102, v103
	v_cvt_pk_bf16_f32 v99, v100, v101
	v_cvt_pk_bf16_f32 v100, v118, v119
	v_cvt_pk_bf16_f32 v101, v122, v123
	v_cvt_pk_bf16_f32 v102, v120, v121
	v_cvt_pk_bf16_f32 v103, v124, v125
	s_waitcnt vmcnt(7)
	v_mfma_f32_16x16x32_bf16 v[68:71], v[104:107], v[96:99], v[68:71]
	v_mfma_f32_16x16x32_bf16 v[40:43], v[104:107], v[100:103], v[40:43]
	s_waitcnt vmcnt(6)
	v_mfma_f32_16x16x32_bf16 v[76:79], v[108:111], v[96:99], v[76:79]
	v_mfma_f32_16x16x32_bf16 v[48:51], v[108:111], v[100:103], v[48:51]
	s_waitcnt vmcnt(5)
	v_mfma_f32_16x16x32_bf16 v[72:75], v[212:215], v[96:99], v[72:75]
	v_mfma_f32_16x16x32_bf16 v[52:55], v[212:215], v[100:103], v[52:55]
	s_waitcnt vmcnt(4)
	v_mfma_f32_16x16x32_bf16 v[88:91], v[216:219], v[96:99], v[88:91]
	v_mfma_f32_16x16x32_bf16 v[60:63], v[216:219], v[100:103], v[60:63]
	s_waitcnt vmcnt(3)
	v_mfma_f32_16x16x32_bf16 v[92:95], v[220:223], v[96:99], v[92:95]
	v_mfma_f32_16x16x32_bf16 v[56:59], v[220:223], v[100:103], v[56:59]
	s_waitcnt vmcnt(2)
	v_mfma_f32_16x16x32_bf16 v[80:83], v[224:227], v[96:99], v[80:83]
	v_mfma_f32_16x16x32_bf16 v[44:47], v[224:227], v[100:103], v[44:47]
	s_waitcnt vmcnt(1)
	v_mfma_f32_16x16x32_bf16 v[84:87], v[228:231], v[96:99], v[84:87]
	v_mfma_f32_16x16x32_bf16 v[36:39], v[228:231], v[100:103], v[36:39]
	s_waitcnt vmcnt(0)
	v_mfma_f32_16x16x32_bf16 v[64:67], v[232:235], v[96:99], v[64:67]
	v_mfma_f32_16x16x32_bf16 v[32:35], v[232:235], v[100:103], v[32:35]
